# MLA attention loop: 16x16x32 row-sum MFMA (4 acc VGPRs), first two V fragment pairs hoisted to QK start with counted lgkmcnt waits, 4-slot V ring so one barrier per key tile
# speedup vs baseline: 1.0170x; 1.0068x over previous
; #define SLOAD(i, k0) do { st_[i].vs = *reinterpret_cast<const bf16x8*>(&Vh[(size_t)((k0) + sr) * LDK + sc]); \
;     st_[i].ks = *reinterpret_cast<const bf16x8*>(&Kh[(size_t)((k0) + sr) * LDK + sc]); \
;     if (DQ == 96) st_[i].kr = *reinterpret_cast<const bf16x8*>(&Kr[(size_t)((k0) + sr2) * 32 + sc2]); } while (0)
; #define SWRITE(b, i) do { *(bf16x8*)(V_lds + (b) * SHM_V + vst0) = st_[i].vs; *(bf16x8*)(K_lds + (b) * SHM_K + kst0) = st_[i].ks; \
;     if (DQ == 96) { if (tid < 256) *(bf16x8*)(K_lds + (b) * SHM_K + kst2) = st_[i].kr; } } while (0)
; #define SWAIT() do { if (DQ == 96) asm volatile("s_waitcnt vmcnt(3)" ::: "memory"); else asm volatile("s_waitcnt vmcnt(2)" ::: "memory"); } while (0)
; #define SLOAD(i, k0) do { st_[i].vs = *reinterpret_cast<const bf16x8*>(&Vh[(size_t)((k0) + sr) * LDK + sc]); \
;     st_[i].ks = *reinterpret_cast<const bf16x8*>(&Kh[(size_t)((k0) + sr) * LDK + sc]); \
;     if (DQ == 96) st_[i].kr = *reinterpret_cast<const bf16x8*>(&Kr[(size_t)((k0) + sr2) * 32 + sc2]); } while (0)
; #define SWRITE(b, i) do { *(bf16x8*)(V_lds + (b) * SHM_V + vst0) = st_[i].vs; *(bf16x8*)(K_lds + (b) * SHM_K + kst0) = st_[i].ks; \
;     if (DQ == 96) { if (tid < 256) *(bf16x8*)(K_lds + (b) * SHM_K + kst2) = st_[i].kr; } } while (0)
; __device__ __forceinline__ float row_max32(const f32x16& p0, const f32x16& p1) {
;     float pmax = p0[0];
; #pragma unroll
;     for (int r = 1; r < 16; ++r) pmax = fmaxf(pmax, p0[r]);
; #pragma unroll
;     for (int r = 0; r < 16; ++r) pmax = fmaxf(pmax, p1[r]);
;     auto rr = __builtin_amdgcn_permlane32_swap(__float_as_uint(pmax), __float_as_uint(pmax), false, false);
;     return fmaxf(__uint_as_float(rr[0]), __uint_as_float(rr[1]));
; }
; template <int DQ, bool WIN, int LDQ, int LDK> ...
;     ...
;     SLOAD(SE, KBASE(0)); SLOAD(SO, KBASE(1));
;     SWAIT(); SWRITE(0, SE); __syncthreads();
;     qkt<DQ>(pA0, pA1, K_lds, qr, zero16, r32, hi);
;     if (WIN) win_mask(pA0, pA1, qrow - KBASE(0), hi);
;     { const float pm = row_max32(pA0, pA1); m_ref = (pm > -1e37f) ? pm : 0.f;
; #pragma unroll
;       for (int r = 0; r < 16; ++r) { minit[r] = -m_ref; pA0[r] -= m_ref; pA1[r] -= m_ref; } }
;     exp16(pA0);
;     if (2 < NT) SLOAD(SE, KBASE(2));
;     SWAIT(); SWRITE(1, SO); __syncthreads();
.LBB0_1088:
	s_or_b64 exec, exec, s[16:17]
	v_and_b32_e32 v188, 31, v80
	s_movk_i32 s16, 0xd0
	v_mad_u32_u24 v0, v188, s16, 0
	v_add_u32_e32 v191, v0, v112
	s_waitcnt lgkmcnt(0)
	s_barrier
	ds_read_b128 v[0:3], v191 offset:16384
	ds_read_b128 v[52:55], v191 offset:16416
	s_waitcnt lgkmcnt(1)
	v_mfma_f32_32x32x16_bf16 v[16:31], v[0:3], v[134:137], 0
	ds_read_b128 v[0:3], v191 offset:23040
	ds_read_b128 v[56:59], v191 offset:23072
	v_lshl_or_b32 v50, v50, 1, v44
	v_mov_b32_e32 v51, v45
	v_lshl_add_u64 v[50:51], s[6:7], 0, v[50:51]
	s_mov_b64 s[16:17], 0x80000
	s_waitcnt lgkmcnt(1)
	v_mfma_f32_32x32x16_bf16 v[0:15], v[0:3], v[134:137], 0
	v_mfma_f32_32x32x16_bf16 v[16:31], v[52:55], v[130:133], v[16:31]
	s_waitcnt lgkmcnt(0)
	v_mfma_f32_32x32x16_bf16 v[0:15], v[56:59], v[130:133], v[0:15]
	ds_read_b128 v[52:55], v191 offset:16448
	ds_read_b128 v[56:59], v191 offset:16480
	s_waitcnt lgkmcnt(1)
	v_mfma_f32_32x32x16_bf16 v[16:31], v[52:55], v[126:129], v[16:31]
	ds_read_b128 v[52:55], v191 offset:23104
	ds_read_b128 v[60:63], v191 offset:23136
	s_waitcnt lgkmcnt(2)
	v_mfma_f32_32x32x16_bf16 v[16:31], v[56:59], v[122:125], v[16:31]
	v_lshl_add_u64 v[56:57], v[50:51], 0, s[16:17]
	v_add_co_u32_e32 v50, vcc, 0x80000, v50
	s_mov_b32 s16, 0xfcf0bdc2
	s_nop 0
	v_addc_co_u32_e32 v51, vcc, 0, v51, vcc
	v_add_co_u32_e32 v46, vcc, 0x2000, v46
	s_waitcnt lgkmcnt(1)
	v_mfma_f32_32x32x16_bf16 v[0:15], v[52:55], v[126:129], v[0:15]
	v_addc_co_u32_e32 v47, vcc, 0, v47, vcc
	ds_read_b128 v[52:55], v191 offset:16512
	ds_read_b128 v[64:67], v191 offset:16544
	global_load_dwordx4 v[138:141], v[56:57], off offset:128
	global_load_dwordx4 v[142:145], v[50:51], off
	global_load_dwordx4 v[146:149], v[46:47], off
	s_waitcnt lgkmcnt(1)
	v_mfma_f32_32x32x16_bf16 v[16:31], v[52:55], v[118:121], v[16:31]
	ds_read_b128 v[50:53], v191 offset:23168
	ds_read_b128 v[54:57], v191 offset:23200
	s_waitcnt vmcnt(3)
	ds_write_b128 v192, v[36:39] offset:8192
	ds_write_b128 v193, v[40:43] offset:29696
	v_add_u32_e32 v36, v48, v49
	v_mfma_f32_32x32x16_bf16 v[0:15], v[60:63], v[122:125], v[0:15]
	s_waitcnt lgkmcnt(4)
	v_mfma_f32_32x32x16_bf16 v[16:31], v[64:67], v[114:117], v[16:31]
	s_waitcnt lgkmcnt(3)
	v_mfma_f32_32x32x16_bf16 v[0:15], v[50:53], v[118:121], v[0:15]
	s_nop 9
	v_max_f32_e32 v46, v17, v17
	v_max_f32_e32 v47, v16, v16
	v_max_f32_e32 v46, v47, v46
	v_max3_f32 v46, v46, v18, v19
	v_max3_f32 v46, v46, v20, v21
	v_max3_f32 v46, v46, v22, v23
	v_max3_f32 v46, v46, v24, v25
	s_waitcnt lgkmcnt(2)
	v_mfma_f32_32x32x16_bf16 v[0:15], v[54:57], v[114:117], v[0:15]
	v_max3_f32 v46, v46, v26, v27
	v_max3_f32 v46, v46, v28, v29
	v_max3_f32 v46, v46, v30, v31
	s_nop 8
	v_max3_f32 v46, v46, v0, v1
	v_max3_f32 v46, v46, v2, v3
	v_max3_f32 v46, v46, v4, v5
	v_max3_f32 v46, v46, v6, v7
	v_max3_f32 v46, v46, v8, v9
	v_max3_f32 v46, v46, v10, v11
	v_max3_f32 v46, v46, v12, v13
	v_max3_f32 v46, v46, v14, v15
	v_mov_b32_e32 v47, v46
	s_nop 1
	v_permlane32_swap_b32_e32 v46, v47
	v_max_f32_e32 v47, v47, v47
	v_max_f32_e32 v46, v46, v46
	v_max_f32_e32 v46, v46, v47
	v_cmp_lt_f32_e32 vcc, s16, v46
	s_and_saveexec_b64 s[16:17], s[4:5]
	s_xor_b64 s[4:5], exec, s[16:17]
	v_add_u32_e32 v36, v48, v49
	s_andn2_saveexec_b64 s[4:5], s[4:5]
	v_add_u32_e32 v37, 0, v36
	ds_write_b128 v37, v[32:35] offset:29824
	s_or_b64 exec, exec, s[4:5]
	v_and_b32_e32 v189, 63, v80
	v_cndmask_b32_e32 v32, 0, v46, vcc
	v_sub_f32_e32 v65, v1, v32
	v_lshlrev_b32_e32 v1, 4, v189
	s_lshr_b32 s4, s20, 5
	s_and_b32 s16, s18, 0xffffffe0
	v_sub_f32_e32 v66, v2, v32
	v_sub_f32_e32 v64, v0, v32
	v_lshlrev_b32_e32 v0, 3, v189
	v_and_b32_e32 v1, 0xc0, v1
	v_lshlrev_b32_e32 v2, 1, v189
	v_and_or_b32 v1, v0, 24, v1
	v_and_b32_e32 v2, 32, v2
	v_and_b32_e32 v0, 0x100, v0
	s_cmp_lg_u32 0, -1
	v_or3_b32 v0, v1, v2, v0
	s_cselect_b32 s5, 0, 0
	s_and_b32 s4, s4, 15
	v_add_u32_e32 v194, s5, v0
	s_lshl_b32 s21, s4, 8
	s_addk_i32 s5, 0x2000
	s_add_u32 s10, s10, 0x10800000
	s_addc_u32 s11, s11, 0
	v_sub_f32_e32 v16, v16, v32
	v_sub_f32_e32 v17, v17, v32
	v_sub_f32_e32 v18, v18, v32
	v_sub_f32_e32 v19, v19, v32
	v_sub_f32_e32 v20, v20, v32
	v_sub_f32_e32 v21, v21, v32
	v_sub_f32_e32 v22, v22, v32
	v_sub_f32_e32 v23, v23, v32
	v_sub_f32_e32 v24, v24, v32
	v_sub_f32_e32 v25, v25, v32
	v_sub_f32_e32 v26, v26, v32
	v_sub_f32_e32 v27, v27, v32
	v_sub_f32_e32 v28, v28, v32
	v_sub_f32_e32 v29, v29, v32
	v_sub_f32_e32 v30, v30, v32
	v_sub_f32_e32 v31, v31, v32
	v_add_lshl_u32 v2, v82, v81, 1
	s_add_u32 s4, s21, s0
	v_exp_f32_e32 v161, v16
	v_exp_f32_e32 v196, v17
	v_exp_f32_e32 v158, v18
	v_exp_f32_e32 v168, v19
	v_exp_f32_e32 v159, v20
	v_exp_f32_e32 v169, v21
	v_exp_f32_e32 v160, v22
	v_exp_f32_e32 v195, v23
	v_exp_f32_e32 v150, v24
	v_exp_f32_e32 v154, v25
	v_exp_f32_e32 v151, v26
	v_exp_f32_e32 v155, v27
	v_exp_f32_e32 v152, v28
	v_exp_f32_e32 v156, v29
	v_exp_f32_e32 v153, v30
	v_exp_f32_e32 v157, v31
	v_sub_f32_e32 v67, v3, v32
	v_add_u32_e32 v190, s5, v0
	v_or_b32_e32 v112, 0x4000, v2
	s_addc_u32 s5, 0, s1
	v_and_b32_e32 v3, 7, v80
	v_lshl_add_u64 v[162:163], s[10:11], 0, v[112:113]
	v_lshl_add_u64 v[0:1], s[4:5], 0, v[44:45]
	v_lshlrev_b32_e32 v112, 4, v3
	v_xor_b32_e32 v48, 0x80000000, v32
	v_lshl_add_u64 v[164:165], v[0:1], 0, v[112:113]
	v_add_u32_e32 v112, 0x3000, v2
	v_mov_b32_e32 v0, 0
	v_mov_b32_e32 v49, v48
	v_mov_b32_e32 v50, v48
	v_mov_b32_e32 v51, v48
	v_mov_b32_e32 v52, v48
	v_mov_b32_e32 v53, v48
	v_mov_b32_e32 v54, v48
	v_mov_b32_e32 v55, v48
	v_mov_b32_e32 v56, v48
	v_mov_b32_e32 v57, v48
	v_mov_b32_e32 v58, v48
	v_mov_b32_e32 v59, v48
	v_mov_b32_e32 v60, v48
	v_mov_b32_e32 v61, v48
	v_mov_b32_e32 v62, v48
	v_mov_b32_e32 v63, v48
; #define SBAR() __builtin_amdgcn_sched_barrier(0)
; #define SLOAD(i, k0) do { st_[i].vs = *reinterpret_cast<const bf16x8*>(&Vh[(size_t)((k0) + sr) * LDK + sc]); \
;     st_[i].ks = *reinterpret_cast<const bf16x8*>(&Kh[(size_t)((k0) + sr) * LDK + sc]); \
;     if (DQ == 96) st_[i].kr = *reinterpret_cast<const bf16x8*>(&Kr[(size_t)((k0) + sr2) * 32 + sc2]); } while (0)
; #define SWRITE(b, i) do { *(bf16x8*)(V_lds + (b) * SHM_V + vst0) = st_[i].vs; *(bf16x8*)(K_lds + (b) * SHM_K + kst0) = st_[i].ks; \
;     if (DQ == 96) { if (tid < 256) *(bf16x8*)(K_lds + (b) * SHM_K + kst2) = st_[i].kr; } } while (0)
; #define SWAIT() do { if (DQ == 96) asm volatile("s_waitcnt vmcnt(3)" ::: "memory"); else asm volatile("s_waitcnt vmcnt(2)" ::: "memory"); } while (0)
; #define SLOAD(i, k0) do { st_[i].vs = *reinterpret_cast<const bf16x8*>(&Vh[(size_t)((k0) + sr) * LDK + sc]); \
;     st_[i].ks = *reinterpret_cast<const bf16x8*>(&Kh[(size_t)((k0) + sr) * LDK + sc]); \
;     if (DQ == 96) st_[i].kr = *reinterpret_cast<const bf16x8*>(&Kr[(size_t)((k0) + sr2) * 32 + sc2]); } while (0)
; #define SWRITE(b, i) do { *(bf16x8*)(V_lds + (b) * SHM_V + vst0) = st_[i].vs; *(bf16x8*)(K_lds + (b) * SHM_K + kst0) = st_[i].ks; \
;     if (DQ == 96) { if (tid < 256) *(bf16x8*)(K_lds + (b) * SHM_K + kst2) = st_[i].kr; } } while (0)
; #define SWAIT() do { if (DQ == 96) asm volatile("s_waitcnt vmcnt(3)" ::: "memory"); else asm volatile("s_waitcnt vmcnt(2)" ::: "memory"); } while (0)
; template <int DQ, bool WIN, int LDQ, int LDK> ...
;     ...
;     auto lsum_upd = [&]() {
;         lsum = __builtin_amdgcn_mfma_f32_32x32x16_bf16(pa0, ones8, lsum, 0, 0, 0);
;         lsum = __builtin_amdgcn_mfma_f32_32x32x16_bf16(pa1, ones8, lsum, 0, 0, 0);
;         lsum = __builtin_amdgcn_mfma_f32_32x32x16_bf16(pa2, ones8, lsum, 0, 0, 0);
;         lsum = __builtin_amdgcn_mfma_f32_32x32x16_bf16(pa3, ones8, lsum, 0, 0, 0);
;     };
;     ...
;     { const float pm = row_max32(pA0, pA1); m_ref = (pm > -1e37f) ? pm : 0.f;
; #pragma unroll
;       for (int r = 0; r < 16; ++r) { minit[r] = -m_ref; pA0[r] -= m_ref; pA1[r] -= m_ref; } }
;     exp16(pA0);
;     if (2 < NT) SLOAD(SE, KBASE(2));
;     SWAIT(); SWRITE(1, SO); __syncthreads();
; #pragma unroll 1
;     for (int j = 1; j + 1 < NT; j += 2) {
;         SBAR(); qkt<DQ>(pB0, pB1, K_lds + SHM_K, qr, minit, r32, hi);
;         finish(pA0, pA1); SBAR();
	v_sub_f32_e32 v79, v15, v32
	v_sub_f32_e32 v78, v14, v32
	v_sub_f32_e32 v77, v13, v32
	v_sub_f32_e32 v76, v12, v32
	v_sub_f32_e32 v75, v11, v32
	v_sub_f32_e32 v74, v10, v32
	v_sub_f32_e32 v73, v9, v32
	v_sub_f32_e32 v72, v8, v32
	v_sub_f32_e32 v71, v7, v32
	v_sub_f32_e32 v70, v6, v32
	v_sub_f32_e32 v69, v5, v32
	v_sub_f32_e32 v68, v4, v32
	s_mov_b32 s17, -1
	v_lshl_add_u64 v[166:167], s[10:11], 0, v[112:113]
	v_add_u32_e32 v112, 0, v36
	v_mov_b32_e32 v1, v0
	v_mov_b32_e32 v2, v0
	v_mov_b32_e32 v3, v0
	v_mov_b32_e32 v4, v0
	v_mov_b32_e32 v5, v0
	v_mov_b32_e32 v6, v0
	v_mov_b32_e32 v7, v0
	v_mov_b32_e32 v8, v0
	v_mov_b32_e32 v9, v0
	v_mov_b32_e32 v10, v0
	v_mov_b32_e32 v11, v0
	v_mov_b32_e32 v12, v0
	v_mov_b32_e32 v13, v0
	v_mov_b32_e32 v14, v0
	v_mov_b32_e32 v15, v0
	v_mov_b32_e32 v16, v0
	v_mov_b32_e32 v17, v0
	v_mov_b32_e32 v18, v0
	v_mov_b32_e32 v19, v0
	v_mov_b32_e32 v20, v0
	v_mov_b32_e32 v21, v0
	v_mov_b32_e32 v22, v0
	v_mov_b32_e32 v23, v0
	v_mov_b32_e32 v24, v0
	v_mov_b32_e32 v25, v0
	v_mov_b32_e32 v26, v0
	v_mov_b32_e32 v27, v0
	v_mov_b32_e32 v28, v0
	v_mov_b32_e32 v29, v0
	v_mov_b32_e32 v30, v0
	v_mov_b32_e32 v31, v0
	v_mov_b32_e32 v32, v0
	v_mov_b32_e32 v33, v0
	v_mov_b32_e32 v34, v0
	v_mov_b32_e32 v35, v0
	v_lshrrev_b32_e32 v36, 4, v189
	v_xor_b32_e32 v36, v36, v189
	v_not_b32_e32 v36, v36
	v_bfe_i32 v36, v36, 0, 1
	v_and_b32_e32 v36, 0x3f803f80, v36
	v_mov_b32_e32 v37, v36
	v_mov_b32_e32 v38, v36
	v_mov_b32_e32 v39, v36
	v_mov_b32_e32 v40, v0
	v_mov_b32_e32 v41, v0
	v_mov_b32_e32 v42, v0
	v_mov_b32_e32 v43, v0
	v_mov_b32_e32 v44, v0
	v_mov_b32_e32 v45, v0
	v_mov_b32_e32 v46, v0
	v_mov_b32_e32 v47, v0
	v_xor_b32_e32 v192, 0xc000, v192
	s_waitcnt lgkmcnt(0)
	s_barrier
	s_branch .LBB0_1094
.LBB0_1093:
	s_or_b64 exec, exec, s[18:19]
	v_xor_b32_e32 v192, 0xc000, v192
	v_xor_b32_e32 v194, 0xc000, v194
	v_xor_b32_e32 v190, 0xc000, v190
	s_waitcnt vmcnt(0)
	v_exp_f32_e32 v161, v96
	v_exp_f32_e32 v196, v97
	v_mfma_f32_16x16x32_bf16 v[32:35], v[80:83], v[36:39], v[32:35]
	v_exp_f32_e32 v158, v98
	v_exp_f32_e32 v168, v99
	v_exp_f32_e32 v159, v100
	v_exp_f32_e32 v169, v101
	v_exp_f32_e32 v160, v102
	v_exp_f32_e32 v195, v103
	v_exp_f32_e32 v154, v105
	v_mfma_f32_16x16x32_bf16 v[32:35], v[84:87], v[36:39], v[32:35]
	v_exp_f32_e32 v155, v107
	v_exp_f32_e32 v156, v109
	v_exp_f32_e32 v157, v111
	s_mov_b64 s[34:35], 0x2000
	s_mov_b64 s[18:19], 0x80000
	v_lshl_add_u64 v[162:163], v[162:163], 0, s[34:35]
	v_lshl_add_u64 v[164:165], v[164:165], 0, s[18:19]
	v_mfma_f32_16x16x32_bf16 v[32:35], v[88:91], v[36:39], v[32:35]
	v_lshl_add_u64 v[166:167], v[166:167], 0, s[34:35]
	s_and_b64 vcc, exec, s[4:5]
	s_waitcnt lgkmcnt(0)
	s_barrier
	v_mfma_f32_16x16x32_bf16 v[32:35], v[92:95], v[36:39], v[32:35]
	v_exp_f32_e32 v150, v104
	v_exp_f32_e32 v151, v106
	v_exp_f32_e32 v152, v108
	v_exp_f32_e32 v153, v110
	s_cbranch_vccnz .LBB0_1100
.LBB0_1094:
	ds_read_b64_tr_b16 v[40:41], v194 offset:0
	ds_read_b64_tr_b16 v[42:43], v194 offset:0x400
	ds_read_b64_tr_b16 v[44:45], v194 offset:0x800
	ds_read_b64_tr_b16 v[46:47], v194 offset:0xc00
	ds_read_b128 v[198:201], v191 offset:36352
	ds_read_b128 v[80:83], v191 offset:29696
	ds_read_b128 v[202:205], v191 offset:29728
	v_exp_f32_e32 v72, v72
	v_exp_f32_e32 v73, v73
	v_exp_f32_e32 v74, v74
	s_waitcnt lgkmcnt(1)
	v_mfma_f32_32x32x16_bf16 v[96:111], v[80:83], v[134:137], v[48:63]
	v_exp_f32_e32 v75, v75
	v_exp_f32_e32 v197, v64
	v_exp_f32_e32 v206, v77
	v_exp_f32_e32 v207, v78
	v_exp_f32_e32 v208, v79
	v_mfma_f32_32x32x16_bf16 v[80:95], v[198:201], v[134:137], v[48:63]
	ds_read_b128 v[198:201], v191 offset:36384
	s_waitcnt lgkmcnt(1)
	v_mfma_f32_32x32x16_bf16 v[96:111], v[202:205], v[130:133], v[96:111]
	s_waitcnt lgkmcnt(0)
	v_mfma_f32_32x32x16_bf16 v[80:95], v[198:201], v[130:133], v[80:95]
	ds_read_b128 v[198:201], v191 offset:29760
	ds_read_b128 v[202:205], v191 offset:36416
	s_waitcnt lgkmcnt(1)
	v_mfma_f32_32x32x16_bf16 v[96:111], v[198:201], v[126:129], v[96:111]
	s_waitcnt lgkmcnt(0)
	v_mfma_f32_32x32x16_bf16 v[80:95], v[202:205], v[126:129], v[80:95]
	ds_read_b128 v[198:201], v191 offset:29792
	ds_read_b128 v[202:205], v191 offset:36448
	s_waitcnt lgkmcnt(1)
	v_mfma_f32_32x32x16_bf16 v[96:111], v[198:201], v[122:125], v[96:111]
	s_waitcnt lgkmcnt(0)
	v_mfma_f32_32x32x16_bf16 v[80:95], v[202:205], v[122:125], v[80:95]
	ds_read_b128 v[198:201], v191 offset:29824
	ds_read_b128 v[202:205], v191 offset:36480
	s_waitcnt lgkmcnt(1)
	v_mfma_f32_32x32x16_bf16 v[96:111], v[198:201], v[118:121], v[96:111]
	s_waitcnt lgkmcnt(0)
	v_mfma_f32_32x32x16_bf16 v[80:95], v[202:205], v[118:121], v[80:95]
	ds_read_b128 v[198:201], v191 offset:29856
	ds_read_b128 v[202:205], v191 offset:36512
	s_waitcnt lgkmcnt(1)
	v_mfma_f32_32x32x16_bf16 v[96:111], v[198:201], v[114:117], v[96:111]
	v_exp_f32_e32 v198, v65
	v_exp_f32_e32 v199, v66
	v_exp_f32_e32 v200, v67
	v_exp_f32_e32 v201, v68
	v_cvt_pk_bf16_f32 v68, v161, v196
	s_waitcnt lgkmcnt(0)
; #define SBAR() __builtin_amdgcn_sched_barrier(0)
; template <int D0> __device__ __forceinline__ void pv_one(f32x16& od, int vb, bf16x8 pa0, bf16x8 pa1, bf16x8 pa2, bf16x8 pa3) {
;     const s16x4 l0 = tr_read<v_rd_off(D0, 0, 0)>(vb), h0 = tr_read<v_rd_off(D0, 0, 1)>(vb), l1 = tr_read<v_rd_off(D0, 1, 0)>(vb), h1 = tr_read<v_rd_off(D0, 1, 1)>(vb);
;     const s16x4 l2 = tr_read<v_rd_off(D0, 2, 0)>(vb), h2 = tr_read<v_rd_off(D0, 2, 1)>(vb), l3 = tr_read<v_rd_off(D0, 3, 0)>(vb), h3 = tr_read<v_rd_off(D0, 3, 1)>(vb);
;     asm volatile("s_waitcnt lgkmcnt(0)" ::: "memory"); SBAR();
;     ...
;     od = __builtin_amdgcn_mfma_f32_32x32x16_bf16(pa0, PK(l0, h0), od, 0, 0, 0);
;     od = __builtin_amdgcn_mfma_f32_32x32x16_bf16(pa1, PK(l1, h1), od, 0, 0, 0);
;     od = __builtin_amdgcn_mfma_f32_32x32x16_bf16(pa2, PK(l2, h2), od, 0, 0, 0);
;     od = __builtin_amdgcn_mfma_f32_32x32x16_bf16(pa3, PK(l3, h3), od, 0, 0, 0);
	v_mfma_f32_32x32x16_bf16 v[80:95], v[202:205], v[114:117], v[80:95]
	v_exp_f32_e32 v202, v69
	v_exp_f32_e32 v203, v70
	v_exp_f32_e32 v204, v71
	v_exp_f32_e32 v205, v76
	v_cvt_pk_bf16_f32 v69, v158, v168
	v_cvt_pk_bf16_f32 v70, v159, v169
	v_cvt_pk_bf16_f32 v71, v160, v195
	v_cvt_pk_bf16_f32 v64, v150, v154
	v_cvt_pk_bf16_f32 v65, v151, v155
	v_cvt_pk_bf16_f32 v66, v152, v156
	v_cvt_pk_bf16_f32 v67, v153, v157
	v_cvt_pk_bf16_f32 v76, v197, v198
	v_cvt_pk_bf16_f32 v77, v199, v200
	v_cvt_pk_bf16_f32 v78, v201, v202
	v_cvt_pk_bf16_f32 v79, v203, v204
	v_cvt_pk_bf16_f32 v72, v72, v73
	v_cvt_pk_bf16_f32 v73, v74, v75
	v_cvt_pk_bf16_f32 v74, v205, v206
	v_cvt_pk_bf16_f32 v75, v207, v208
	v_lshl_add_u64 v[168:169], s[26:27], 0, v[164:165]
	s_mov_b32 s4, 0x218c0000
	v_add_co_u32_e32 v150, vcc, s4, v168
	s_nop 1
	v_addc_co_u32_e32 v151, vcc, 0, v169, vcc
	global_load_dwordx4 v[154:157], v[150:151], off offset:128
	global_load_dwordx4 v[158:161], v[150:151], off
	v_lshl_add_u64 v[150:151], s[26:27], 0, v[166:167]
	global_load_dwordx4 v[150:153], v[150:151], off
	ds_read_b64_tr_b16 v[204:205], v194 offset:0x1000
	ds_read_b64_tr_b16 v[206:207], v194 offset:0x1400
	ds_read_b64_tr_b16 v[208:209], v194 offset:0x1800
	ds_read_b64_tr_b16 v[210:211], v194 offset:0x1c00
	ds_read_b64_tr_b16 v[196:197], v194 offset:0x200
	ds_read_b64_tr_b16 v[198:199], v194 offset:0x600
	ds_read_b64_tr_b16 v[200:201], v194 offset:0xa00
	ds_read_b64_tr_b16 v[202:203], v194 offset:0xe00
	s_nop 0
	v_mfma_f32_32x32x16_bf16 v[0:15], v[68:71], v[40:43], v[0:15]
	v_mfma_f32_32x32x16_bf16 v[0:15], v[64:67], v[44:47], v[0:15]
	s_waitcnt lgkmcnt(6)
	v_mfma_f32_32x32x16_bf16 v[0:15], v[76:79], v[204:207], v[0:15]
	ds_read_b64_tr_b16 v[204:205], v194 offset:0x1200
	ds_read_b64_tr_b16 v[206:207], v194 offset:0x1600
	s_waitcnt lgkmcnt(6)
	v_mfma_f32_32x32x16_bf16 v[0:15], v[72:75], v[208:211], v[0:15]
	ds_read_b64_tr_b16 v[208:209], v194 offset:0x1a00
	ds_read_b64_tr_b16 v[210:211], v194 offset:0x1e00
	s_waitcnt lgkmcnt(0)
	v_mfma_f32_32x32x16_bf16 v[16:31], v[68:71], v[196:199], v[16:31]
	s_waitcnt vmcnt(3)
	s_waitcnt vmcnt(5)
	ds_write_b128 v192, v[138:141]
	s_waitcnt vmcnt(4)
	ds_write_b128 v193, v[142:145] offset:16384
	v_mfma_f32_32x32x16_bf16 v[16:31], v[64:67], v[200:203], v[16:31]
	v_mfma_f32_32x32x16_bf16 v[16:31], v[76:79], v[204:207], v[16:31]
	v_mfma_f32_32x32x16_bf16 v[16:31], v[72:75], v[208:211], v[16:31]
	s_and_saveexec_b64 s[4:5], s[40:41]
	s_cbranch_execz .LBB0_1096
	s_waitcnt vmcnt(3)
	ds_write_b128 v112, v[146:149] offset:16512
; #define SBAR() __builtin_amdgcn_sched_barrier(0)
; #define SLOAD(i, k0) do { st_[i].vs = *reinterpret_cast<const bf16x8*>(&Vh[(size_t)((k0) + sr) * LDK + sc]); \
;     st_[i].ks = *reinterpret_cast<const bf16x8*>(&Kh[(size_t)((k0) + sr) * LDK + sc]); \
;     if (DQ == 96) st_[i].kr = *reinterpret_cast<const bf16x8*>(&Kr[(size_t)((k0) + sr2) * 32 + sc2]); } while (0)
; #define SWRITE(b, i) do { *(bf16x8*)(V_lds + (b) * SHM_V + vst0) = st_[i].vs; *(bf16x8*)(K_lds + (b) * SHM_K + kst0) = st_[i].ks; \
;     if (DQ == 96) { if (tid < 256) *(bf16x8*)(K_lds + (b) * SHM_K + kst2) = st_[i].kr; } } while (0)
; #define SWAIT() do { if (DQ == 96) asm volatile("s_waitcnt vmcnt(3)" ::: "memory"); else asm volatile("s_waitcnt vmcnt(2)" ::: "memory"); } while (0)
; #define SWAIT() do { if (DQ == 96) asm volatile("s_waitcnt vmcnt(3)" ::: "memory"); else asm volatile("s_waitcnt vmcnt(2)" ::: "memory"); } while (0)
; template <int D0> __device__ __forceinline__ void pv_one(f32x16& od, int vb, bf16x8 pa0, bf16x8 pa1, bf16x8 pa2, bf16x8 pa3) {
;     const s16x4 l0 = tr_read<v_rd_off(D0, 0, 0)>(vb), h0 = tr_read<v_rd_off(D0, 0, 1)>(vb), l1 = tr_read<v_rd_off(D0, 1, 0)>(vb), h1 = tr_read<v_rd_off(D0, 1, 1)>(vb);
;     const s16x4 l2 = tr_read<v_rd_off(D0, 2, 0)>(vb), h2 = tr_read<v_rd_off(D0, 2, 1)>(vb), l3 = tr_read<v_rd_off(D0, 3, 0)>(vb), h3 = tr_read<v_rd_off(D0, 3, 1)>(vb);
;     asm volatile("s_waitcnt lgkmcnt(0)" ::: "memory"); SBAR();
;     ...
;     od = __builtin_amdgcn_mfma_f32_32x32x16_bf16(pa0, PK(l0, h0), od, 0, 0, 0);
;     od = __builtin_amdgcn_mfma_f32_32x32x16_bf16(pa1, PK(l1, h1), od, 0, 0, 0);
;     od = __builtin_amdgcn_mfma_f32_32x32x16_bf16(pa2, PK(l2, h2), od, 0, 0, 0);
;     od = __builtin_amdgcn_mfma_f32_32x32x16_bf16(pa3, PK(l3, h3), od, 0, 0, 0);
; template <int DQ, bool WIN, int LDQ, int LDK> ...
;     ...
;         lsum_upd();
;         if (WIN) win_mask(pB0, pB1, qrow - KBASE(j), hi);
;         exp16(pB0);
;         __syncthreads();
;         SBAR(); qkt<DQ>(pA0, pA1, K_lds, qr, minit, r32, hi);
;         finish(pB0, pB1); SBAR();
;         if (j + 3 < NT) SLOAD(SE, KBASE(j + 3)); SBAR();
;         pv(vb0 + SHM_V);
;         __syncthreads(); SWAIT(); SWRITE(1, SO);
;         lsum_upd();
;         if (WIN) win_mask(pA0, pA1, qrow - KBASE(j + 1), hi);
;         exp16(pA0);
;         __syncthreads();
;     }
.LBB0_1096:
	s_or_b64 exec, exec, s[4:5]
	s_add_i32 s17, s17, 2
	v_exp_f32_e32 v195, v96
	v_mfma_f32_16x16x32_bf16 v[32:35], v[68:71], v[36:39], v[32:35]
	v_exp_f32_e32 v204, v97
	v_exp_f32_e32 v205, v98
	v_exp_f32_e32 v206, v99
	v_exp_f32_e32 v207, v100
	v_exp_f32_e32 v208, v101
	v_exp_f32_e32 v209, v102
	v_exp_f32_e32 v210, v103
	v_mfma_f32_16x16x32_bf16 v[32:35], v[64:67], v[36:39], v[32:35]
	v_exp_f32_e32 v211, v104
	v_exp_f32_e32 v212, v105
	v_exp_f32_e32 v213, v106
	v_exp_f32_e32 v214, v107
	v_exp_f32_e32 v215, v108
	v_exp_f32_e32 v216, v109
	v_exp_f32_e32 v217, v110
	v_mfma_f32_16x16x32_bf16 v[32:35], v[76:79], v[36:39], v[32:35]
	v_exp_f32_e32 v218, v111
	s_waitcnt lgkmcnt(0)
	s_barrier
	v_mfma_f32_16x16x32_bf16 v[32:35], v[72:75], v[36:39], v[32:35]
	ds_read_b64_tr_b16 v[40:41], v190 offset:0
	ds_read_b64_tr_b16 v[42:43], v190 offset:0x400
	ds_read_b64_tr_b16 v[44:45], v190 offset:0x800
	ds_read_b64_tr_b16 v[46:47], v190 offset:0xc00
	ds_read_b128 v[196:199], v191 offset:23040
	ds_read_b128 v[64:67], v191 offset:16384
	ds_read_b128 v[200:203], v191 offset:16416
	v_exp_f32_e32 v95, v95
	v_exp_f32_e32 v219, v88
	v_exp_f32_e32 v220, v89
	s_waitcnt lgkmcnt(1)
	v_mfma_f32_32x32x16_bf16 v[96:111], v[64:67], v[134:137], v[48:63]
	v_exp_f32_e32 v221, v90
	v_exp_f32_e32 v222, v91
	v_exp_f32_e32 v223, v92
	v_exp_f32_e32 v224, v93
	v_exp_f32_e32 v225, v94
	v_mfma_f32_32x32x16_bf16 v[64:79], v[196:199], v[134:137], v[48:63]
	ds_read_b128 v[196:199], v191 offset:23072
	s_waitcnt lgkmcnt(1)
	v_mfma_f32_32x32x16_bf16 v[96:111], v[200:203], v[130:133], v[96:111]
	s_waitcnt lgkmcnt(0)
	v_mfma_f32_32x32x16_bf16 v[64:79], v[196:199], v[130:133], v[64:79]
	ds_read_b128 v[196:199], v191 offset:16448
	ds_read_b128 v[200:203], v191 offset:23104
	s_waitcnt lgkmcnt(1)
	v_mfma_f32_32x32x16_bf16 v[96:111], v[196:199], v[126:129], v[96:111]
	s_waitcnt lgkmcnt(0)
	v_mfma_f32_32x32x16_bf16 v[64:79], v[200:203], v[126:129], v[64:79]
	ds_read_b128 v[196:199], v191 offset:16480
	ds_read_b128 v[200:203], v191 offset:23136
	s_waitcnt lgkmcnt(1)
	v_mfma_f32_32x32x16_bf16 v[96:111], v[196:199], v[122:125], v[96:111]
	s_waitcnt lgkmcnt(0)
	v_mfma_f32_32x32x16_bf16 v[64:79], v[200:203], v[122:125], v[64:79]
	ds_read_b128 v[196:199], v191 offset:16512
	ds_read_b128 v[200:203], v191 offset:23168
	s_waitcnt lgkmcnt(1)
	v_mfma_f32_32x32x16_bf16 v[96:111], v[196:199], v[118:121], v[96:111]
	s_waitcnt lgkmcnt(0)
	v_mfma_f32_32x32x16_bf16 v[64:79], v[200:203], v[118:121], v[64:79]
	ds_read_b128 v[196:199], v191 offset:16544
	ds_read_b128 v[200:203], v191 offset:23200
	s_waitcnt lgkmcnt(1)
	v_mfma_f32_32x32x16_bf16 v[96:111], v[196:199], v[114:117], v[96:111]
	v_exp_f32_e32 v196, v80
	v_exp_f32_e32 v197, v81
	v_exp_f32_e32 v198, v82
	v_exp_f32_e32 v199, v83
	v_cvt_pk_bf16_f32 v80, v195, v204
	v_cvt_pk_bf16_f32 v81, v205, v206
	v_cvt_pk_bf16_f32 v82, v207, v208
	s_waitcnt lgkmcnt(0)
	v_mfma_f32_32x32x16_bf16 v[64:79], v[200:203], v[114:117], v[64:79]
	v_exp_f32_e32 v200, v84
	v_exp_f32_e32 v201, v85
	v_exp_f32_e32 v202, v86
	v_exp_f32_e32 v203, v87
	v_cvt_pk_bf16_f32 v83, v209, v210
	v_cvt_pk_bf16_f32 v84, v211, v212
	v_cvt_pk_bf16_f32 v85, v213, v214
	v_cvt_pk_bf16_f32 v86, v215, v216
	v_cvt_pk_bf16_f32 v87, v217, v218
	v_cvt_pk_bf16_f32 v88, v196, v197
	v_cvt_pk_bf16_f32 v89, v198, v199
	v_cvt_pk_bf16_f32 v90, v200, v201
	v_cvt_pk_bf16_f32 v91, v202, v203
	v_cvt_pk_bf16_f32 v92, v219, v220
	v_cvt_pk_bf16_f32 v93, v221, v222
	v_cvt_pk_bf16_f32 v94, v223, v224
	v_cvt_pk_bf16_f32 v95, v225, v95
	s_cmpk_gt_u32 s17, 0x7c
	s_cselect_b64 s[4:5], -1, 0
	s_and_b64 vcc, exec, s[4:5]
	s_cbranch_vccnz .LBB0_1098
	v_add_co_u32_e32 v142, vcc, 0x21900000, v168
	s_waitcnt vmcnt(3)
	v_lshl_add_u64 v[146:147], s[26:27], 0, v[162:163]
	v_addc_co_u32_e32 v143, vcc, 0, v169, vcc
	global_load_dwordx4 v[138:141], v[142:143], off offset:128
	s_nop 0
	global_load_dwordx4 v[142:145], v[142:143], off
	s_nop 0
	global_load_dwordx4 v[146:149], v[146:147], off
.LBB0_1098:
	ds_read_b64_tr_b16 v[204:205], v190 offset:0x1000
	ds_read_b64_tr_b16 v[206:207], v190 offset:0x1400
	ds_read_b64_tr_b16 v[208:209], v190 offset:0x1800
	ds_read_b64_tr_b16 v[210:211], v190 offset:0x1c00
	ds_read_b64_tr_b16 v[196:197], v190 offset:0x200
	ds_read_b64_tr_b16 v[198:199], v190 offset:0x600
	ds_read_b64_tr_b16 v[200:201], v190 offset:0xa00
	ds_read_b64_tr_b16 v[202:203], v190 offset:0xe00
	s_nop 0
	v_mfma_f32_32x32x16_bf16 v[0:15], v[80:83], v[40:43], v[0:15]
	v_mfma_f32_32x32x16_bf16 v[0:15], v[84:87], v[44:47], v[0:15]
	s_waitcnt lgkmcnt(6)
	v_mfma_f32_32x32x16_bf16 v[0:15], v[88:91], v[204:207], v[0:15]
	ds_read_b64_tr_b16 v[204:205], v190 offset:0x1200
	ds_read_b64_tr_b16 v[206:207], v190 offset:0x1600
	s_waitcnt lgkmcnt(6)
	v_mfma_f32_32x32x16_bf16 v[0:15], v[92:95], v[208:211], v[0:15]
	ds_read_b64_tr_b16 v[208:209], v190 offset:0x1a00
	ds_read_b64_tr_b16 v[210:211], v190 offset:0x1e00
	s_waitcnt lgkmcnt(0)
	v_mfma_f32_32x32x16_bf16 v[16:31], v[80:83], v[196:199], v[16:31]
	s_waitcnt vmcnt(3)
	s_waitcnt vmcnt(2)
	ds_write_b128 v192, v[154:157] offset:8192
	s_waitcnt vmcnt(1)
	ds_write_b128 v193, v[158:161] offset:29696
	v_mfma_f32_32x32x16_bf16 v[16:31], v[84:87], v[200:203], v[16:31]
	v_mfma_f32_32x32x16_bf16 v[16:31], v[88:91], v[204:207], v[16:31]
	v_mfma_f32_32x32x16_bf16 v[16:31], v[92:95], v[208:211], v[16:31]
	s_and_saveexec_b64 s[18:19], s[40:41]
	s_cbranch_execz .LBB0_1093
	s_waitcnt vmcnt(0)
	ds_write_b128 v112, v[150:153] offset:29824
	s_branch .LBB0_1093
